# XCD-local phase seams (G1->G2, G2->N2, G4->N3, N3->G5, G5->G6), guard: every workgroup on the XCC of workgroup (id & 7)
# speedup vs baseline: 1.0036x; 1.0036x over previous
_Z8mega_fwd4Args:
	s_load_dwordx8 s[4:11], s[0:1], 0x80
	s_load_dword s3, s[0:1], 0xc0
	s_load_dwordx4 s[92:95], s[0:1], 0xa0
	s_load_dwordx2 s[50:51], s[0:1], 0xb8
	v_and_b32_e32 v226, 0x3ff, v0
	v_cmp_gt_u32_e32 vcc, 2, v226
	v_readfirstlane_b32 s33, v226
	s_waitcnt lgkmcnt(0)
	v_writelane_b32 v252, s4, 0
	s_nop 1
	v_writelane_b32 v252, s5, 1
	v_writelane_b32 v252, s6, 2
	v_writelane_b32 v252, s7, 3
	v_writelane_b32 v252, s8, 4
	v_writelane_b32 v252, s9, 5
	v_writelane_b32 v252, s10, 6
	v_writelane_b32 v252, s11, 7
	s_add_u32 s10, s0, 0xb8
	s_addc_u32 s11, s1, 0
	s_and_saveexec_b64 s[4:5], vcc
	v_lshl_add_u32 v1, v226, 2, 0
	v_add_u32_e32 v1, 0x23fe0, v1
	v_mov_b32_e32 v2, 0
	ds_write_b32 v1, v2
	s_or_b64 exec, exec, s[4:5]
	s_mov_b64 s[22:23], s[94:95]
	s_waitcnt lgkmcnt(0)
	s_barrier
	s_add_u32 s25, s22, 0x1000
	s_getreg_b32 s4, hwreg(HW_REG_XCC_ID, 0, 4)
	s_addc_u32 s27, s23, 0
	s_and_b32 s29, s4, 15
	v_cmp_eq_u32_e64 s[6:7], 0, v226
	s_mov_b64 s[4:5], exec
	s_nop 0
	v_writelane_b32 v252, s6, 8
	s_nop 1
	v_writelane_b32 v252, s7, 9
	s_and_b64 s[6:7], s[4:5], s[6:7]
	s_mov_b64 exec, s[6:7]
	s_cbranch_execz .LBB0_4
	s_lshl_b32 s6, s29, 8
	s_add_u32 s6, s25, s6
	s_addc_u32 s7, s27, 0
	v_mov_b32_e32 v1, 1
	v_mov_b64_e32 v[2:3], s[6:7]
	flat_atomic_add v[2:3], v1 offset:1024
	s_cmp_lt_u32 s2, 8
	s_cbranch_scc0 .Lxcc_ok
	s_lshl_b32 s6, s2, 2
	s_add_u32 s6, s22, s6
	s_addc_u32 s7, s23, 0
	s_add_u32 s6, s6, 0x4000
	s_addc_u32 s7, s7, 0
	v_mov_b32_e32 v6, s29
	v_add_u32_e32 v6, 1, v6
	v_mov_b64_e32 v[4:5], s[6:7]
	flat_atomic_add v[4:5], v6

.LBB0_101:
	v_writelane_b32 v253, s20, 34
	s_nop 1
	v_writelane_b32 v253, s21, 35
	v_writelane_b32 v253, s18, 36
	s_nop 1
	v_writelane_b32 v253, s19, 37
	v_writelane_b32 v253, s16, 38
	s_nop 1
	v_writelane_b32 v253, s17, 39
	v_writelane_b32 v253, s14, 40
	s_nop 1
	v_writelane_b32 v253, s15, 41
	v_writelane_b32 v253, s12, 42
	s_nop 1
	v_writelane_b32 v253, s13, 43
	v_writelane_b32 v253, s10, 44
	s_nop 1
	v_writelane_b32 v253, s11, 45
	s_or_b64 exec, exec, s[0:1]
	v_cmp_eq_u32_e32 vcc, 0, v226
	s_and_saveexec_b64 s[0:1], vcc
	s_cbranch_execz .Lxt_done
	s_and_b32 s3, s2, 7
	s_lshl_b32 s3, s3, 2
	s_add_i32 s3, s3, 0x4000
	v_mov_b32_e32 v0, s3
	global_load_dword v0, v0, s[94:95] sc1
	s_getreg_b32 s38, hwreg(HW_REG_XCC_ID, 0, 4)
	s_add_i32 s38, s38, 1
	s_waitcnt vmcnt(0)
	v_cmp_ne_u32_e32 vcc, s38, v0
	s_and_b64 exec, exec, vcc
	s_cbranch_execz .Lxt_done
	v_mov_b32_e32 v0, 0
	v_mov_b32_e32 v1, 1
	global_atomic_add v0, v1, s[94:95] offset:3072
	s_waitcnt vmcnt(0)
.Lxt_done:
	s_or_b64 exec, exec, s[0:1]
	s_lshr_b32 s3, s33, 6
	s_and_b32 s0, s2, 7
	s_lshl_b32 s0, s0, 5
	s_lshr_b32 s1, s2, 3
	s_add_i32 s0, s0, s1
	s_lshl_b32 s0, s0, 3
	s_add_i32 s38, s3, s0
	s_lshl_b32 s40, s50, 3
	s_add_u32 s30, s92, 0x4000000
	v_readlane_b32 s8, v252, 10
	s_addc_u32 s31, s93, 0
	v_readlane_b32 s20, v252, 22
	v_readlane_b32 s21, v252, 23
	s_add_u32 s0, s20, 0x1000
	s_addc_u32 s1, s21, 0
	v_writelane_b32 v253, s0, 46
	s_cmp_lt_i32 s38, 0x8000
	v_readlane_b32 s22, v252, 24
	v_writelane_b32 v253, s1, 47
	s_cselect_b64 s[0:1], -1, 0
	v_writelane_b32 v253, s0, 48
	s_cmpk_lt_i32 s38, 0x2a00
	v_readlane_b32 s23, v252, 25
	v_writelane_b32 v253, s1, 49
	s_cselect_b64 s[0:1], -1, 0
	v_writelane_b32 v253, s0, 50
	v_readlane_b32 s10, v252, 12
	v_readlane_b32 s12, v252, 14
	v_writelane_b32 v253, s1, 51
	s_mul_i32 s0, s3, 0x4400
	s_add_i32 s33, s0, 0
	s_add_u32 s0, s94, 0x2900000
	s_addc_u32 s1, s95, 0
	v_writelane_b32 v253, s0, 52
	v_readlane_b32 s11, v252, 13
	v_readlane_b32 s13, v252, 15
	v_writelane_b32 v253, s1, 53
	s_add_u32 s0, s94, 0x2600000
	s_addc_u32 s1, s95, 0
	v_writelane_b32 v253, s0, 54
	v_readlane_b32 s68, v252, 26
	v_readlane_b32 s69, v252, 27
	v_writelane_b32 v253, s1, 55
	s_add_u32 s0, s94, 0x2400000
	s_addc_u32 s1, s95, 0
	v_writelane_b32 v253, s0, 56
	v_readlane_b32 s14, v252, 16
	v_readlane_b32 s15, v252, 17
	v_writelane_b32 v253, s1, 57
	s_add_u32 s0, s94, 0x2700000
	s_addc_u32 s1, s95, 0
	v_writelane_b32 v253, s0, 58
	s_cmpk_lt_i32 s2, 0xb00
	v_readlane_b32 s72, v252, 30
	v_writelane_b32 v253, s1, 59
	s_cselect_b64 s[0:1], -1, 0
	v_writelane_b32 v253, s0, 60
	s_ashr_i32 s51, s2, 31
	s_ashr_i32 s57, s50, 31
	v_writelane_b32 v253, s1, 61
	s_lshr_b32 s0, s51, 29
	s_add_i32 s0, s2, s0
	s_ashr_i32 s24, s0, 3
	s_and_b32 s0, s0, -8
	s_sub_i32 s25, s2, s0
	s_cmpk_lt_i32 s2, 0x200
	s_cselect_b64 s[0:1], -1, 0
	v_writelane_b32 v253, s0, 62
	s_lshl_b32 s26, s25, 6
	s_add_i32 s22, s38, 1
	v_writelane_b32 v253, s1, 63
	s_lshl_b32 s0, s50, 4
	s_cmpk_lt_i32 s2, 0x100
	v_writelane_b32 v254, s0, 0
	s_cselect_b64 s[0:1], -1, 0
	v_writelane_b32 v254, s0, 1
	s_and_b32 s23, s2, 1
	s_lshl_b32 s27, s25, 5
	v_writelane_b32 v254, s1, 2
	s_ashr_i32 s0, s2, 7
	s_lshl_b32 s1, s0, 1
	s_or_b32 s10, s1, s23
	s_lshl_b32 s0, s0, 6
	s_bfe_u32 s1, s2, 0x60001
	s_or_b32 s12, s0, s1
	s_mov_b32 s0, s10
	s_ashr_i32 s11, s10, 31
	v_writelane_b32 v254, s0, 3
	s_ashr_i32 s13, s12, 31
	v_readlane_b32 s73, v252, 31
	v_writelane_b32 v254, s1, 4
	s_lshl_b64 s[0:1], s[10:11], 19
	v_writelane_b32 v254, s0, 5
	v_readlane_b32 s16, v252, 18
	v_readlane_b32 s17, v252, 19
	v_writelane_b32 v254, s1, 6
	s_mov_b32 s0, s12
	v_writelane_b32 v254, s0, 7
	v_readlane_b32 s18, v252, 20
	v_readlane_b32 s19, v252, 21
	v_writelane_b32 v254, s1, 8
	s_lshl_b64 s[0:1], s[12:13], 19
	v_writelane_b32 v254, s0, 9
	s_cmpk_lt_i32 s2, 0x60
	v_readlane_b32 s9, v252, 11
	v_writelane_b32 v254, s1, 10
	s_cselect_b64 s[0:1], -1, 0
	v_writelane_b32 v254, s0, 11
	s_lshl_b32 s23, s2, 6
	s_ashr_i32 s28, s2, 3
	v_writelane_b32 v254, s1, 12
	s_and_b32 s0, s23, 0x1c0
	v_writelane_b32 v254, s0, 13
	s_lshl_b32 s0, s28, 11
	s_lshl_b32 s1, s28, 12
	s_bitset1_b32 s0, 10
	s_addk_i32 s1, 0xc800
	s_cmp_lt_i32 s28, 8
	s_cselect_b32 s0, s0, s1
	s_ashr_i32 s1, s0, 31
	s_lshl_b64 s[0:1], s[0:1], 11
	v_writelane_b32 v254, s0, 14
	v_readlane_b32 s76, v252, 34
	v_readlane_b32 s77, v252, 35
	v_writelane_b32 v254, s1, 15
	s_lshl_b32 s0, s28, 9
	v_writelane_b32 v254, s0, 16
	s_add_u32 s0, s68, 0x1000
	s_addc_u32 s1, s69, 0
	v_writelane_b32 v254, s0, 17
	s_cmp_lt_i32 s25, 0
	s_mov_b32 s53, 0
	v_writelane_b32 v254, s1, 18
	s_movk_i32 s1, 0x161
	s_cselect_b32 s1, s1, 0x160
	s_mul_i32 s0, s25, 0x41
	s_mul_i32 s1, s25, s1
	s_mul_i32 s25, s25, 33
	s_cselect_b32 s0, s0, s26
	s_cselect_b32 s25, s25, s27
	s_add_i32 s1, s1, s24
	s_mul_hi_i32 s26, s1, 0x2e8ba2e9
	s_lshr_b32 s27, s26, 31
	s_ashr_i32 s26, s26, 5
	s_add_i32 s26, s26, s27
	s_mul_i32 s27, s26, 0xb0
	s_sub_i32 s1, s1, s27
	s_bfe_u32 s27, s1, 0x3001c
	s_add_i32 s27, s1, s27
	s_and_b32 s28, s27, 0xfff8
	s_add_i32 s0, s0, s24
	s_sub_i32 s1, s1, s28
	s_ashr_i32 s28, s0, 31
	s_lshr_b32 s28, s28, 27
	s_add_i32 s28, s0, s28
	s_and_b32 s29, s28, 0xffe0
	s_sub_i32 s0, s0, s29
	s_bfe_i32 s29, s0, 0x80000
	s_bfe_u32 s29, s29, 0x3000c
	s_add_i32 s29, s0, s29
	s_and_b32 s34, s29, 0xf8
	s_sub_i32 s34, s0, s34
	s_add_i32 s0, s25, s24
	s_ashr_i32 s24, s0, 31
	s_lshr_b32 s24, s24, 22
	s_add_i32 s24, s0, s24
	s_and_b32 s25, s24, 0xfffffc00
	s_sub_i32 s35, s0, s25
	s_abs_i32 s25, s40
	v_cvt_f32_u32_e32 v0, s25
	s_sub_i32 s0, 0, s25
	s_sext_i32_i16 s1, s1
	v_readlane_b32 s48, v253, 44
	v_rcp_iflag_f32_e32 v0, v0
	v_readlane_b32 s60, v253, 42
	v_readlane_b32 s62, v253, 40
	v_readlane_b32 s76, v253, 38
	v_mul_f32_e32 v0, 0x4f7ffffe, v0
	v_cvt_u32_f32_e32 v0, v0
	v_readlane_b32 s20, v253, 34
	v_mov_b32_e32 v177, 0
	v_mov_b32_e32 v228, 0x358637bd
	v_readfirstlane_b32 s36, v0
	s_mul_i32 s0, s0, s36
	s_mul_hi_u32 s0, s36, s0
	s_add_i32 s36, s36, s0
	s_lshl_b32 s0, s26, 3
	s_sext_i32_i16 s26, s27
	s_add_i32 s12, s0, s1
	s_ashr_i32 s0, s26, 3
	v_writelane_b32 v254, s0, 19
	s_lshr_b32 s0, s26, 3
	s_bfe_i64 s[0:1], s[0:1], 0x100000
	s_lshl_b64 s[0:1], s[0:1], 19
	v_writelane_b32 v254, s0, 20
	s_sext_i32_i8 s26, s34
	s_mov_b32 s10, s12
	v_writelane_b32 v254, s1, 21
	s_ashr_i32 s0, s28, 5
	s_bfe_i32 s1, s29, 0x80000
	s_lshl_b32 s0, s0, 3
	s_sext_i32_i16 s1, s1
	s_add_i32 s14, s0, s26
	s_lshr_b32 s0, s1, 3
	s_ashr_i32 s7, s1, 3
	s_bfe_i64 s[0:1], s[0:1], 0x100000
	s_lshl_b64 s[0:1], s[0:1], 19
	v_writelane_b32 v254, s0, 22
	s_ashr_i32 s13, s12, 31
	s_ashr_i32 s15, s14, 31
	v_writelane_b32 v254, s1, 23
	s_ashr_i32 s0, s24, 10
	s_lshl_b32 s26, s0, 3
	s_sub_i32 s0, 2, s26
	s_min_u32 s27, s0, 8
	s_lshr_b32 s0, s36, 17
	v_writelane_b32 v254, s10, 24
	s_mul_i32 s1, s0, s25
	s_sub_i32 s1, 0x8000, s1
	v_writelane_b32 v254, s11, 25
	s_lshl_b64 s[10:11], s[12:13], 19
	v_writelane_b32 v254, s10, 26
	s_bfe_i32 s24, s50, 0x1001c
	s_add_i32 s28, s0, 1
	s_sub_i32 s29, s1, s25
	v_writelane_b32 v254, s11, 27
	s_lshl_b64 s[10:11], s[14:15], 19
	s_cmp_ge_u32 s1, s25
	s_cselect_b32 s0, s28, s0
	s_cselect_b32 s1, s29, s1
	s_add_i32 s28, s0, 1
	s_sub_i32 s29, s1, s25
	s_cmp_ge_u32 s1, s25
	s_cselect_b32 s0, s28, s0
	v_writelane_b32 v254, s10, 28
	s_cselect_b32 s1, s29, s1
	s_xor_b32 s0, s0, s24
	v_writelane_b32 v254, s11, 29
	s_sub_i32 s10, s0, s24
	s_and_b32 s28, s10, 3
	s_or_b32 s29, s1, s28
	s_cmp_eq_u32 s29, 0
	s_cselect_b64 s[0:1], -1, 0
	s_cmp_lg_u32 s29, 0
	s_cselect_b64 s[12:13], -1, 0
	s_abs_i32 s29, s10
	v_cvt_f32_u32_e32 v0, s29
	s_sub_i32 s34, 0, s29
	v_writelane_b32 v254, s12, 30
	s_mul_i32 s72, s10, s38
	v_rcp_iflag_f32_e32 v0, v0
	v_writelane_b32 v254, s13, 31
	v_cndmask_b32_e64 v227, 0, 1, s[0:1]
	v_mov_b32_e32 v229, 0x260
	v_mul_f32_e32 v0, 0x4f7ffffe, v0
	v_cvt_u32_f32_e32 v0, v0
	v_mov_b32_e32 v230, 1
	v_mov_b64_e32 v[178:179], 0xb00
	v_mov_b64_e32 v[180:181], 0xaff
	v_readfirstlane_b32 s37, v0
	s_mul_i32 s34, s34, s37
	s_mul_hi_u32 s34, s37, s34
	s_add_i32 s37, s37, s34
	s_lshr_b32 s34, s37, 21
	s_mul_i32 s34, s34, s29
	s_sub_i32 s34, 0x800, s34
	s_sub_i32 s37, s34, s29
	s_cmp_ge_u32 s34, s29
	s_cselect_b32 s34, s37, s34
	s_sub_i32 s37, s34, s29
	s_cmp_ge_u32 s34, s29
	s_cselect_b32 s29, s37, s34
	s_cmp_lg_u32 s29, 0
	s_cselect_b64 s[12:13], -1, 0
	v_writelane_b32 v254, s12, 32
	s_cmpk_gt_i32 s72, 0x3fff
	v_mov_b64_e32 v[182:183], 0x200
	v_writelane_b32 v254, s13, 33
	s_cselect_b64 s[12:13], -1, 0
	s_add_i32 s29, s72, 0xffffc000
	s_lshr_b32 s29, s29, 12
	s_ashr_i32 s73, s72, 31
	v_writelane_b32 v254, s12, 34
	s_add_i32 s11, s29, 8
	s_lshr_b32 s29, s73, 21
	v_writelane_b32 v254, s13, 35
	s_add_i32 s29, s72, s29
	v_writelane_b32 v254, s11, 36
	s_ashr_i32 s11, s29, 11
	s_cmp_gt_i32 s10, 0
	s_cselect_b64 s[12:13], -1, 0
	s_lshr_b32 s29, s36, 18
	s_mul_i32 s34, s29, s25
	s_sub_i32 s34, 0x4000, s34
	s_add_i32 s36, s29, 1
	s_sub_i32 s37, s34, s25
	s_cmp_ge_u32 s34, s25
	s_cselect_b32 s29, s36, s29
	s_cselect_b32 s34, s37, s34
	s_add_i32 s36, s29, 1
	s_cmp_ge_u32 s34, s25
	s_cselect_b32 s25, s36, s29
	s_xor_b32 s25, s25, s24
	v_writelane_b32 v254, s11, 37
	s_sub_i32 s11, s25, s24
	v_cvt_f32_i32_e32 v0, s11
	s_mul_i32 s24, s11, s40
	s_and_b32 s25, s11, 1
	s_sub_i32 s24, s25, s24
	v_rcp_iflag_f32_e32 v1, v0
	v_writelane_b32 v254, s12, 38
	s_cmpk_eq_i32 s24, 0xc000
	s_mov_b32 s24, 0x44800000
	v_mul_f32_e32 v1, 0x44800000, v1
	v_trunc_f32_e32 v1, v1
	v_writelane_b32 v254, s13, 39
	v_fma_f32 v2, -v1, v0, s24
	s_cselect_b64 s[12:13], -1, 0
	s_ashr_i32 s24, s11, 30
	s_or_b32 s29, s24, 1
	v_cmp_ge_f32_e64 s[24:25], |v2|, |v0|
	v_cvt_i32_f32_e32 v0, v1
	s_and_b64 s[24:25], s[24:25], exec
	v_cvt_f32_ubyte0_e32 v1, s27
	v_rcp_iflag_f32_e32 v2, v1
	v_readfirstlane_b32 s25, v0
	v_cvt_f32_i32_e32 v0, s35
	s_cselect_b32 s24, s29, 0
	s_add_i32 s24, s25, s24
	s_mul_i32 s24, s24, s11
	s_and_b32 s24, s24, 0xffff
	v_mul_f32_e32 v2, v0, v2
	v_writelane_b32 v254, s12, 40
	s_cmpk_eq_i32 s24, 0x400
	v_trunc_f32_e32 v2, v2
	v_writelane_b32 v254, s13, 41
	s_cselect_b64 s[12:13], -1, 0
	s_ashr_i32 s24, s35, 30
	v_fma_f32 v0, -v2, v1, v0
	s_or_b32 s29, s24, 1
	v_cmp_ge_f32_e64 s[24:25], |v0|, v1
	v_cvt_i32_f32_e32 v0, v2
	s_and_b64 s[24:25], s[24:25], exec
	s_cselect_b32 s24, s29, 0
	v_writelane_b32 v254, s12, 42
	v_readfirstlane_b32 s25, v0
	s_add_i32 s24, s25, s24
	s_mul_i32 s25, s24, s27
	s_sub_i32 s25, s35, s25
	s_mul_i32 s27, s10, s40
	s_sext_i32_i16 s25, s25
	s_sub_i32 s28, s28, s27
	s_add_i32 s16, s26, s25
	s_bfe_i64 s[26:27], s[24:25], 0x100000
	v_writelane_b32 v254, s13, 43
	s_lshl_b64 s[12:13], s[26:27], 19
	v_writelane_b32 v254, s12, 44
	s_ashr_i32 s17, s16, 31
	s_add_i32 s28, s28, 0x8000
	v_writelane_b32 v254, s13, 45
	s_mov_b32 s12, s16
	v_writelane_b32 v254, s12, 46
	s_sext_i32_i16 s0, s24
	v_writelane_b32 v255, s0, 0
	v_writelane_b32 v254, s13, 47
	s_lshl_b64 s[12:13], s[16:17], 19
	v_writelane_b32 v254, s12, 48
	s_cmp_eq_u32 s28, 0
	v_mov_b64_e32 v[184:185], 0x1ff
	v_writelane_b32 v254, s13, 49
	s_cselect_b64 s[12:13], -1, 0
	v_writelane_b32 v254, s12, 50
	s_cmp_lg_u32 s28, 0
	v_mov_b64_e32 v[188:189], 0xff
	v_writelane_b32 v254, s13, 51
	s_cselect_b64 s[12:13], -1, 0
	v_writelane_b32 v254, s12, 52
	s_ashr_i32 s39, s38, 31
	v_bfrev_b32_e32 v231, 0.5
	v_writelane_b32 v254, s13, 53
	s_lshl_b64 s[12:13], s[38:39], 11
	s_add_u32 s16, s92, s12
	v_writelane_b32 v254, s12, 54
	s_addc_u32 s17, s93, s13
	s_ashr_i32 s41, s40, 31
	v_writelane_b32 v254, s13, 55
	v_writelane_b32 v254, s16, 56
	s_lshl_b64 s[12:13], s[40:41], 11
	v_writelane_b32 v255, s40, 1
	v_writelane_b32 v254, s17, 57
	s_lshl_b64 s[16:17], s[72:73], 11
	s_add_u32 s18, s92, s16
	s_addc_u32 s19, s93, s17
	v_writelane_b32 v254, s18, 58
	v_writelane_b32 v255, s41, 2
	v_mov_b32_e32 v232, 0x100
	v_writelane_b32 v254, s19, 59
	v_writelane_b32 v254, s38, 60
	s_lshl_b64 s[26:27], s[38:39], 12
	s_add_u32 s8, s8, s26
	s_addc_u32 s9, s9, s27
	s_lshl_b64 s[0:1], s[40:41], 12
	v_writelane_b32 v255, s0, 3
	v_writelane_b32 v254, s39, 61
	v_writelane_b32 v254, s8, 62
	v_writelane_b32 v255, s1, 4
	s_add_u32 s0, s16, 0x4b00000
	v_writelane_b32 v255, s0, 5
	v_writelane_b32 v255, s16, 6
	s_addc_u32 s0, s17, 0
	v_readlane_b32 s18, v253, 36
	v_writelane_b32 v255, s17, 7
	v_writelane_b32 v255, s0, 8
	s_lshl_b32 s0, s3, 3
	s_add_i32 s0, s23, s0
	v_writelane_b32 v255, s0, 9
	v_writelane_b32 v255, s11, 10
	s_mul_i32 s0, s11, s22
	v_writelane_b32 v255, s0, 11
	s_mul_hi_i32 s0, s14, 0x160000
	v_writelane_b32 v255, s0, 12
	s_mov_b32 s0, s14
	v_writelane_b32 v255, s0, 13
	v_writelane_b32 v254, s9, 63
	s_mov_b32 s89, 0xf800000
	v_writelane_b32 v255, s1, 14
	s_mul_i32 s0, s14, 0x160000
	v_writelane_b32 v255, s0, 15
	s_mul_hi_i32 s0, s7, 0x160000
	v_writelane_b32 v255, s0, 16
	v_writelane_b32 v255, s7, 17
	s_mul_i32 s0, s7, 0x160000
	v_writelane_b32 v255, s0, 18
	s_lshl_b32 s0, s50, 6
	v_writelane_b32 v255, s0, 19
	s_add_i32 s0, 0, 0x23fe0
	v_writelane_b32 v255, s0, 20
	s_add_i32 s0, 0, 0x23fe4
	v_writelane_b32 v255, s0, 21
	s_add_i32 s0, 0, 0x23ff0
	v_writelane_b32 v255, s0, 22
	s_add_i32 s0, 0, 0x12100
	v_writelane_b32 v255, s0, 23
	v_writelane_b32 v255, s6, 24
	v_writelane_b32 v255, s10, 25
	v_writelane_b32 v255, s72, 26
	s_movk_i32 s28, 0x5800
	s_movk_i32 s29, 0x1600
	v_writelane_b32 v255, s73, 27
	v_writelane_b32 v255, s12, 28
	s_mov_b64 s[0:1], -1
	s_mov_b64 s[24:25], 0x80
	s_mov_b64 s[26:27], 0x100
	s_mov_b64 s[84:85], 0x20000
	s_mov_b32 s88, 0x3b3504f3
	s_mov_b32 s56, 0x3b000000
	s_mov_b32 s14, s53
	v_readlane_b32 s49, v253, 45
	v_readlane_b32 s61, v253, 43
	v_readlane_b32 s63, v253, 41
	v_readlane_b32 s77, v253, 39
	v_readlane_b32 s19, v253, 37
	v_readlane_b32 s21, v253, 35
	v_writelane_b32 v255, s13, 29
	v_readlane_b32 s70, v252, 28
	v_readlane_b32 s71, v252, 29
	v_readlane_b32 s74, v252, 32
	v_readlane_b32 s75, v252, 33
	v_readlane_b32 s78, v252, 36
	v_readlane_b32 s79, v252, 37
	v_readlane_b32 s80, v252, 38
	v_readlane_b32 s81, v252, 39
	v_readlane_b32 s82, v252, 40
	v_readlane_b32 s83, v252, 41
	s_waitcnt lgkmcnt(0)
	s_barrier
	s_branch .LBB0_105
